# state-copy loads in the chunk-state phase issued together (one wait instead of three serialized round trips)
# baseline (speedup 1.0000x reference)
.LBB0_439:
	v_ashrrev_i32_e32 v134, 15, v132
	v_and_b32_e32 v211, 0x7fff, v132
	v_lshlrev_b32_e32 v130, 6, v134
	v_lshlrev_b32_e32 v190, 2, v211
	v_ashrrev_i32_e32 v131, 31, v130
	v_lshl_add_u64 v[98:99], s[22:23], 0, v[190:191]
	v_lshlrev_b64 v[2:3], 17, v[130:131]
	v_or_b32_e32 v128, 1, v130
	v_lshl_add_u64 v[2:3], v[98:99], 0, v[2:3]
	v_ashrrev_i32_e32 v129, 31, v128
	global_load_dword v210, v[2:3], off nt
	v_lshlrev_b64 v[2:3], 17, v[128:129]
	v_or_b32_e32 v126, 2, v130
	v_lshl_add_u64 v[2:3], v[98:99], 0, v[2:3]
	v_ashrrev_i32_e32 v127, 31, v126
	global_load_dword v209, v[2:3], off nt
	v_lshlrev_b64 v[2:3], 17, v[126:127]
	v_or_b32_e32 v124, 3, v130
	v_lshl_add_u64 v[2:3], v[98:99], 0, v[2:3]
	v_ashrrev_i32_e32 v125, 31, v124
	global_load_dword v207, v[2:3], off nt
	v_lshlrev_b64 v[2:3], 17, v[124:125]
	v_or_b32_e32 v122, 4, v130
	v_lshl_add_u64 v[2:3], v[98:99], 0, v[2:3]
	v_ashrrev_i32_e32 v123, 31, v122
	global_load_dword v206, v[2:3], off nt
	v_lshlrev_b64 v[2:3], 17, v[122:123]
	v_or_b32_e32 v120, 5, v130
	v_lshl_add_u64 v[2:3], v[98:99], 0, v[2:3]
	v_ashrrev_i32_e32 v121, 31, v120
	global_load_dword v205, v[2:3], off nt
	v_lshlrev_b64 v[2:3], 17, v[120:121]
	v_or_b32_e32 v118, 6, v130
	v_lshl_add_u64 v[2:3], v[98:99], 0, v[2:3]
	v_ashrrev_i32_e32 v119, 31, v118
	global_load_dword v204, v[2:3], off nt
	v_lshlrev_b64 v[2:3], 17, v[118:119]
	v_or_b32_e32 v116, 7, v130
	v_lshl_add_u64 v[2:3], v[98:99], 0, v[2:3]
	v_ashrrev_i32_e32 v117, 31, v116
	global_load_dword v203, v[2:3], off nt
	v_lshlrev_b64 v[2:3], 17, v[116:117]
	v_or_b32_e32 v114, 8, v130
	v_lshl_add_u64 v[2:3], v[98:99], 0, v[2:3]
	v_ashrrev_i32_e32 v115, 31, v114
	global_load_dword v199, v[2:3], off nt
	v_lshlrev_b64 v[2:3], 17, v[114:115]
	v_or_b32_e32 v112, 9, v130
	v_lshl_add_u64 v[2:3], v[98:99], 0, v[2:3]
	v_ashrrev_i32_e32 v113, 31, v112
	global_load_dword v189, v[2:3], off nt
	v_lshlrev_b64 v[2:3], 17, v[112:113]
	v_or_b32_e32 v110, 10, v130
	v_lshl_add_u64 v[2:3], v[98:99], 0, v[2:3]
	v_ashrrev_i32_e32 v111, 31, v110
	global_load_dword v188, v[2:3], off nt
	v_lshlrev_b64 v[2:3], 17, v[110:111]
	v_or_b32_e32 v108, 11, v130
	v_lshl_add_u64 v[2:3], v[98:99], 0, v[2:3]
	v_ashrrev_i32_e32 v109, 31, v108
	global_load_dword v187, v[2:3], off nt
	v_lshlrev_b64 v[2:3], 17, v[108:109]
	v_or_b32_e32 v106, 12, v130
	v_lshl_add_u64 v[2:3], v[98:99], 0, v[2:3]
	v_ashrrev_i32_e32 v107, 31, v106
	global_load_dword v186, v[2:3], off nt
	v_lshlrev_b64 v[2:3], 17, v[106:107]
	v_or_b32_e32 v104, 13, v130
	v_lshl_add_u64 v[2:3], v[98:99], 0, v[2:3]
	v_ashrrev_i32_e32 v105, 31, v104
	global_load_dword v185, v[2:3], off nt
	v_lshlrev_b64 v[2:3], 17, v[104:105]
	v_or_b32_e32 v102, 14, v130
	v_lshl_add_u64 v[2:3], v[98:99], 0, v[2:3]
	v_ashrrev_i32_e32 v103, 31, v102
	global_load_dword v184, v[2:3], off nt
	v_lshlrev_b64 v[2:3], 17, v[102:103]
	v_or_b32_e32 v100, 15, v130
	v_lshl_add_u64 v[2:3], v[98:99], 0, v[2:3]
	v_ashrrev_i32_e32 v101, 31, v100
	global_load_dword v183, v[2:3], off nt
	v_lshlrev_b64 v[2:3], 17, v[100:101]
	v_or_b32_e32 v96, 16, v130
	v_lshl_add_u64 v[2:3], v[98:99], 0, v[2:3]
	v_ashrrev_i32_e32 v97, 31, v96
	global_load_dword v182, v[2:3], off nt
	v_lshlrev_b64 v[2:3], 17, v[96:97]
	v_or_b32_e32 v94, 17, v130
	v_lshl_add_u64 v[2:3], v[98:99], 0, v[2:3]
	v_ashrrev_i32_e32 v95, 31, v94
	global_load_dword v181, v[2:3], off nt
	v_lshlrev_b64 v[2:3], 17, v[94:95]
	v_or_b32_e32 v92, 18, v130
	v_lshl_add_u64 v[2:3], v[98:99], 0, v[2:3]
	v_ashrrev_i32_e32 v93, 31, v92
	global_load_dword v180, v[2:3], off nt
	v_lshlrev_b64 v[2:3], 17, v[92:93]
	v_or_b32_e32 v90, 19, v130
	v_lshl_add_u64 v[2:3], v[98:99], 0, v[2:3]
	v_ashrrev_i32_e32 v91, 31, v90
	global_load_dword v179, v[2:3], off nt
	v_lshlrev_b64 v[2:3], 17, v[90:91]
	v_or_b32_e32 v88, 20, v130
	v_lshl_add_u64 v[2:3], v[98:99], 0, v[2:3]
	v_ashrrev_i32_e32 v89, 31, v88
	global_load_dword v178, v[2:3], off nt
	v_lshlrev_b64 v[2:3], 17, v[88:89]
	v_or_b32_e32 v86, 21, v130
	v_lshl_add_u64 v[2:3], v[98:99], 0, v[2:3]
	v_ashrrev_i32_e32 v87, 31, v86
	global_load_dword v177, v[2:3], off nt
	v_lshlrev_b64 v[2:3], 17, v[86:87]
	v_or_b32_e32 v84, 22, v130
	v_lshl_add_u64 v[2:3], v[98:99], 0, v[2:3]
	v_ashrrev_i32_e32 v85, 31, v84
	global_load_dword v176, v[2:3], off nt
	v_lshlrev_b64 v[2:3], 17, v[84:85]
	v_or_b32_e32 v82, 23, v130
	v_lshl_add_u64 v[2:3], v[98:99], 0, v[2:3]
	v_ashrrev_i32_e32 v83, 31, v82
	global_load_dword v175, v[2:3], off nt
	v_lshlrev_b64 v[2:3], 17, v[82:83]
	v_or_b32_e32 v80, 24, v130
	v_lshl_add_u64 v[2:3], v[98:99], 0, v[2:3]
	v_ashrrev_i32_e32 v81, 31, v80
	global_load_dword v174, v[2:3], off nt
	v_lshlrev_b64 v[2:3], 17, v[80:81]
	v_or_b32_e32 v78, 25, v130
	v_lshl_add_u64 v[2:3], v[98:99], 0, v[2:3]
	v_ashrrev_i32_e32 v79, 31, v78
	global_load_dword v173, v[2:3], off nt
	v_lshlrev_b64 v[2:3], 17, v[78:79]
	v_or_b32_e32 v76, 26, v130
	v_lshl_add_u64 v[2:3], v[98:99], 0, v[2:3]
	v_ashrrev_i32_e32 v77, 31, v76
	global_load_dword v172, v[2:3], off nt
	v_lshlrev_b64 v[2:3], 17, v[76:77]
	v_or_b32_e32 v74, 27, v130
	v_lshl_add_u64 v[2:3], v[98:99], 0, v[2:3]
	v_ashrrev_i32_e32 v75, 31, v74
	global_load_dword v171, v[2:3], off nt
	v_lshlrev_b64 v[2:3], 17, v[74:75]
	v_or_b32_e32 v72, 28, v130
	v_lshl_add_u64 v[2:3], v[98:99], 0, v[2:3]
	v_ashrrev_i32_e32 v73, 31, v72
	global_load_dword v170, v[2:3], off nt
	v_lshlrev_b64 v[2:3], 17, v[72:73]
	v_or_b32_e32 v70, 29, v130
	v_lshl_add_u64 v[2:3], v[98:99], 0, v[2:3]
	v_ashrrev_i32_e32 v71, 31, v70
	global_load_dword v169, v[2:3], off nt
	v_lshlrev_b64 v[2:3], 17, v[70:71]
	v_or_b32_e32 v68, 30, v130
	v_lshl_add_u64 v[2:3], v[98:99], 0, v[2:3]
	v_ashrrev_i32_e32 v69, 31, v68
	global_load_dword v168, v[2:3], off nt
	v_lshlrev_b64 v[2:3], 17, v[68:69]
	v_or_b32_e32 v66, 31, v130
	v_lshl_add_u64 v[2:3], v[98:99], 0, v[2:3]
	v_ashrrev_i32_e32 v67, 31, v66
	global_load_dword v167, v[2:3], off nt
	v_lshlrev_b64 v[2:3], 17, v[66:67]
	v_or_b32_e32 v64, 32, v130
	v_lshl_add_u64 v[2:3], v[98:99], 0, v[2:3]
	v_ashrrev_i32_e32 v65, 31, v64
	global_load_dword v166, v[2:3], off nt
	v_lshlrev_b64 v[2:3], 17, v[64:65]
	v_or_b32_e32 v62, 33, v130
	v_lshl_add_u64 v[2:3], v[98:99], 0, v[2:3]
	v_ashrrev_i32_e32 v63, 31, v62
	global_load_dword v165, v[2:3], off nt
	v_lshlrev_b64 v[2:3], 17, v[62:63]
	v_or_b32_e32 v60, 34, v130
	v_lshl_add_u64 v[2:3], v[98:99], 0, v[2:3]
	v_ashrrev_i32_e32 v61, 31, v60
	global_load_dword v164, v[2:3], off nt
	v_lshlrev_b64 v[2:3], 17, v[60:61]
	v_or_b32_e32 v58, 35, v130
	v_lshl_add_u64 v[2:3], v[98:99], 0, v[2:3]
	v_ashrrev_i32_e32 v59, 31, v58
	global_load_dword v163, v[2:3], off nt
	v_lshlrev_b64 v[2:3], 17, v[58:59]
	v_or_b32_e32 v56, 36, v130
	v_lshl_add_u64 v[2:3], v[98:99], 0, v[2:3]
	v_ashrrev_i32_e32 v57, 31, v56
	global_load_dword v162, v[2:3], off nt
	v_lshlrev_b64 v[2:3], 17, v[56:57]
	v_or_b32_e32 v54, 37, v130
	v_lshl_add_u64 v[2:3], v[98:99], 0, v[2:3]
	v_ashrrev_i32_e32 v55, 31, v54
	global_load_dword v161, v[2:3], off nt
	v_lshlrev_b64 v[2:3], 17, v[54:55]
	v_or_b32_e32 v52, 38, v130
	v_lshl_add_u64 v[2:3], v[98:99], 0, v[2:3]
	v_ashrrev_i32_e32 v53, 31, v52
	global_load_dword v160, v[2:3], off nt
	v_lshlrev_b64 v[2:3], 17, v[52:53]
	v_or_b32_e32 v50, 39, v130
	v_lshl_add_u64 v[2:3], v[98:99], 0, v[2:3]
	v_ashrrev_i32_e32 v51, 31, v50
	global_load_dword v159, v[2:3], off nt
	v_lshlrev_b64 v[2:3], 17, v[50:51]
	v_or_b32_e32 v48, 40, v130
	v_lshl_add_u64 v[2:3], v[98:99], 0, v[2:3]
	v_ashrrev_i32_e32 v49, 31, v48
	global_load_dword v158, v[2:3], off nt
	v_lshlrev_b64 v[2:3], 17, v[48:49]
	v_or_b32_e32 v46, 41, v130
	v_lshl_add_u64 v[2:3], v[98:99], 0, v[2:3]
	v_ashrrev_i32_e32 v47, 31, v46
	global_load_dword v157, v[2:3], off nt
	v_lshlrev_b64 v[2:3], 17, v[46:47]
	v_or_b32_e32 v44, 42, v130
	v_lshl_add_u64 v[2:3], v[98:99], 0, v[2:3]
	v_ashrrev_i32_e32 v45, 31, v44
	global_load_dword v156, v[2:3], off nt
	v_lshlrev_b64 v[2:3], 17, v[44:45]
	v_or_b32_e32 v42, 43, v130
	v_lshl_add_u64 v[2:3], v[98:99], 0, v[2:3]
	v_ashrrev_i32_e32 v43, 31, v42
	global_load_dword v155, v[2:3], off nt
	v_lshlrev_b64 v[2:3], 17, v[42:43]
	v_or_b32_e32 v40, 44, v130
	v_lshl_add_u64 v[2:3], v[98:99], 0, v[2:3]
	v_ashrrev_i32_e32 v41, 31, v40
	global_load_dword v154, v[2:3], off nt
	v_lshlrev_b64 v[2:3], 17, v[40:41]
	v_or_b32_e32 v38, 45, v130
	v_lshl_add_u64 v[2:3], v[98:99], 0, v[2:3]
	v_ashrrev_i32_e32 v39, 31, v38
	global_load_dword v153, v[2:3], off nt
	v_lshlrev_b64 v[2:3], 17, v[38:39]
	v_or_b32_e32 v36, 46, v130
	v_lshl_add_u64 v[2:3], v[98:99], 0, v[2:3]
	v_ashrrev_i32_e32 v37, 31, v36
	global_load_dword v152, v[2:3], off nt
	v_lshlrev_b64 v[2:3], 17, v[36:37]
	v_or_b32_e32 v34, 47, v130
	v_lshl_add_u64 v[2:3], v[98:99], 0, v[2:3]
	v_ashrrev_i32_e32 v35, 31, v34
	global_load_dword v151, v[2:3], off nt
	v_lshlrev_b64 v[2:3], 17, v[34:35]
	v_or_b32_e32 v32, 48, v130
	v_lshl_add_u64 v[2:3], v[98:99], 0, v[2:3]
	v_ashrrev_i32_e32 v33, 31, v32
	global_load_dword v150, v[2:3], off nt
	v_lshlrev_b64 v[2:3], 17, v[32:33]
	v_or_b32_e32 v30, 49, v130
	v_lshl_add_u64 v[2:3], v[98:99], 0, v[2:3]
	v_ashrrev_i32_e32 v31, 31, v30
	global_load_dword v149, v[2:3], off nt
	v_lshlrev_b64 v[2:3], 17, v[30:31]
	v_or_b32_e32 v28, 50, v130
	v_lshl_add_u64 v[2:3], v[98:99], 0, v[2:3]
	v_ashrrev_i32_e32 v29, 31, v28
	global_load_dword v148, v[2:3], off nt
	v_lshlrev_b64 v[2:3], 17, v[28:29]
	v_or_b32_e32 v26, 51, v130
	v_lshl_add_u64 v[2:3], v[98:99], 0, v[2:3]
	v_ashrrev_i32_e32 v27, 31, v26
	global_load_dword v147, v[2:3], off nt
	v_lshlrev_b64 v[2:3], 17, v[26:27]
	v_or_b32_e32 v24, 52, v130
	v_lshl_add_u64 v[2:3], v[98:99], 0, v[2:3]
	v_ashrrev_i32_e32 v25, 31, v24
	global_load_dword v146, v[2:3], off nt
	v_lshlrev_b64 v[2:3], 17, v[24:25]
	v_or_b32_e32 v22, 53, v130
	v_lshl_add_u64 v[2:3], v[98:99], 0, v[2:3]
	v_ashrrev_i32_e32 v23, 31, v22
	global_load_dword v145, v[2:3], off nt
	v_lshlrev_b64 v[2:3], 17, v[22:23]
	v_or_b32_e32 v20, 54, v130
	v_lshl_add_u64 v[2:3], v[98:99], 0, v[2:3]
	v_ashrrev_i32_e32 v21, 31, v20
	global_load_dword v144, v[2:3], off nt
	v_lshlrev_b64 v[2:3], 17, v[20:21]
	v_or_b32_e32 v18, 55, v130
	v_lshl_add_u64 v[2:3], v[98:99], 0, v[2:3]
	v_ashrrev_i32_e32 v19, 31, v18
	global_load_dword v143, v[2:3], off nt
	v_lshlrev_b64 v[2:3], 17, v[18:19]
	s_waitcnt vmcnt(0)
	v_or_b32_e32 v16, 56, v130
	v_lshl_add_u64 v[2:3], v[98:99], 0, v[2:3]
	v_ashrrev_i32_e32 v17, 31, v16
	global_load_dword v142, v[2:3], off nt
	v_lshlrev_b64 v[2:3], 17, v[16:17]
	v_or_b32_e32 v14, 57, v130
	v_lshl_add_u64 v[2:3], v[98:99], 0, v[2:3]
	v_ashrrev_i32_e32 v15, 31, v14
	global_load_dword v141, v[2:3], off nt
	v_lshlrev_b64 v[2:3], 17, v[14:15]
	v_or_b32_e32 v12, 58, v130
	v_lshl_add_u64 v[2:3], v[98:99], 0, v[2:3]
	v_ashrrev_i32_e32 v13, 31, v12
	global_load_dword v140, v[2:3], off nt
	v_lshlrev_b64 v[2:3], 17, v[12:13]
	v_or_b32_e32 v10, 59, v130
	v_lshl_add_u64 v[2:3], v[98:99], 0, v[2:3]
	v_ashrrev_i32_e32 v11, 31, v10
	global_load_dword v139, v[2:3], off nt
	v_lshlrev_b64 v[2:3], 17, v[10:11]
	v_or_b32_e32 v8, 60, v130
	v_lshl_add_u64 v[2:3], v[98:99], 0, v[2:3]
	v_ashrrev_i32_e32 v9, 31, v8
	global_load_dword v138, v[2:3], off nt
	v_lshlrev_b64 v[2:3], 17, v[8:9]
	v_or_b32_e32 v6, 61, v130
	v_lshl_add_u64 v[2:3], v[98:99], 0, v[2:3]
	v_ashrrev_i32_e32 v7, 31, v6
	global_load_dword v137, v[2:3], off nt
	v_lshlrev_b64 v[2:3], 17, v[6:7]
	v_or_b32_e32 v4, 62, v130
	v_lshl_add_u64 v[2:3], v[98:99], 0, v[2:3]
	v_ashrrev_i32_e32 v5, 31, v4
	global_load_dword v136, v[2:3], off nt
	v_lshlrev_b64 v[2:3], 17, v[4:5]
	v_lshl_add_u64 v[2:3], v[98:99], 0, v[2:3]
	global_load_dword v135, v[2:3], off nt
	v_or_b32_e32 v2, 63, v130
	v_ashrrev_i32_e32 v3, 31, v2
	v_lshlrev_b64 v[192:193], 17, v[2:3]
	v_bfe_u32 v208, v132, 13, 2
	v_lshl_add_u64 v[98:99], v[98:99], 0, v[192:193]
	v_lshl_or_b32 v192, v134, 8, v208
	v_ashrrev_i32_e32 v193, 31, v192
	v_lshl_add_u64 v[192:193], v[192:193], 2, s[76:77]
	global_load_dword v133, v[98:99], off nt
	global_load_dword v226, v[192:193], off
	v_lshl_or_b32 v192, v128, 2, v208
	v_ashrrev_i32_e32 v193, 31, v192
	v_lshl_add_u64 v[192:193], v[192:193], 2, s[76:77]
	global_load_dword v225, v[192:193], off
	v_lshl_or_b32 v192, v126, 2, v208
	v_ashrrev_i32_e32 v193, 31, v192
	v_lshl_add_u64 v[192:193], v[192:193], 2, s[76:77]
	global_load_dword v224, v[192:193], off
	v_lshl_or_b32 v192, v124, 2, v208
	v_ashrrev_i32_e32 v193, 31, v192
	v_lshl_add_u64 v[192:193], v[192:193], 2, s[76:77]
	global_load_dword v223, v[192:193], off
	v_lshl_or_b32 v192, v122, 2, v208
	v_ashrrev_i32_e32 v193, 31, v192
	v_lshl_add_u64 v[192:193], v[192:193], 2, s[76:77]
	global_load_dword v222, v[192:193], off
	v_lshl_or_b32 v192, v120, 2, v208
	v_ashrrev_i32_e32 v193, 31, v192
	v_lshl_add_u64 v[192:193], v[192:193], 2, s[76:77]
	global_load_dword v221, v[192:193], off
	v_lshl_or_b32 v192, v118, 2, v208
	v_ashrrev_i32_e32 v193, 31, v192
	v_lshl_add_u64 v[192:193], v[192:193], 2, s[76:77]
	global_load_dword v220, v[192:193], off
	v_lshl_or_b32 v192, v116, 2, v208
	v_ashrrev_i32_e32 v193, 31, v192
	v_lshl_add_u64 v[192:193], v[192:193], 2, s[76:77]
	global_load_dword v219, v[192:193], off
	v_lshl_or_b32 v192, v114, 2, v208
	v_ashrrev_i32_e32 v193, 31, v192
	v_lshl_add_u64 v[192:193], v[192:193], 2, s[76:77]
	global_load_dword v218, v[192:193], off
	v_lshl_or_b32 v192, v112, 2, v208
	v_ashrrev_i32_e32 v193, 31, v192
	v_lshl_add_u64 v[192:193], v[192:193], 2, s[76:77]
	global_load_dword v217, v[192:193], off
	v_lshl_or_b32 v192, v110, 2, v208
	v_ashrrev_i32_e32 v193, 31, v192
	v_lshl_add_u64 v[192:193], v[192:193], 2, s[76:77]
	global_load_dword v216, v[192:193], off
	v_lshl_or_b32 v192, v108, 2, v208
	v_ashrrev_i32_e32 v193, 31, v192
	v_lshl_add_u64 v[192:193], v[192:193], 2, s[76:77]
	global_load_dword v215, v[192:193], off
	v_lshl_or_b32 v192, v106, 2, v208
	v_ashrrev_i32_e32 v193, 31, v192
	v_lshl_add_u64 v[192:193], v[192:193], 2, s[76:77]
	global_load_dword v214, v[192:193], off
	v_lshl_or_b32 v192, v104, 2, v208
	v_ashrrev_i32_e32 v193, 31, v192
	v_lshl_add_u64 v[192:193], v[192:193], 2, s[76:77]
	global_load_dword v213, v[192:193], off
	v_lshl_or_b32 v192, v102, 2, v208
	v_ashrrev_i32_e32 v193, 31, v192
	v_lshl_add_u64 v[192:193], v[192:193], 2, s[76:77]
	global_load_dword v212, v[192:193], off
	v_lshlrev_b32_e32 v98, 1, v211
	v_mov_b32_e32 v99, v191
	v_lshl_add_u64 v[98:99], s[24:25], 0, v[98:99]
	v_lshl_or_b32 v192, v100, 2, v208
	v_lshlrev_b64 v[130:131], 16, v[130:131]
	v_lshlrev_b64 v[128:129], 16, v[128:129]
	v_lshlrev_b64 v[126:127], 16, v[126:127]
	v_lshlrev_b64 v[124:125], 16, v[124:125]
	v_lshlrev_b64 v[122:123], 16, v[122:123]
	v_lshlrev_b64 v[120:121], 16, v[120:121]
	v_lshlrev_b64 v[118:119], 16, v[118:119]
	v_lshlrev_b64 v[116:117], 16, v[116:117]
	v_lshlrev_b64 v[114:115], 16, v[114:115]
	v_lshlrev_b64 v[112:113], 16, v[112:113]
	v_lshlrev_b64 v[110:111], 16, v[110:111]
	v_lshlrev_b64 v[108:109], 16, v[108:109]
	v_lshlrev_b64 v[106:107], 16, v[106:107]
	v_lshlrev_b64 v[104:105], 16, v[104:105]
	v_lshlrev_b64 v[102:103], 16, v[102:103]
	v_lshlrev_b64 v[100:101], 16, v[100:101]
	v_lshl_add_u64 v[130:131], v[98:99], 0, v[130:131]
	v_lshl_add_u64 v[128:129], v[98:99], 0, v[128:129]
	v_lshl_add_u64 v[126:127], v[98:99], 0, v[126:127]
	s_waitcnt vmcnt(0)
	v_fmac_f32_e32 v210, 0, v226
	v_lshl_add_u64 v[124:125], v[98:99], 0, v[124:125]
	v_lshl_add_u64 v[122:123], v[98:99], 0, v[122:123]
	v_lshl_add_u64 v[120:121], v[98:99], 0, v[120:121]
	v_fmac_f32_e32 v209, v210, v225
	v_lshl_add_u64 v[118:119], v[98:99], 0, v[118:119]
	v_lshl_add_u64 v[116:117], v[98:99], 0, v[116:117]
	v_lshl_add_u64 v[114:115], v[98:99], 0, v[114:115]
	v_fmac_f32_e32 v207, v209, v224
	v_lshl_add_u64 v[112:113], v[98:99], 0, v[112:113]
	v_lshl_add_u64 v[110:111], v[98:99], 0, v[110:111]
	v_lshl_add_u64 v[108:109], v[98:99], 0, v[108:109]
	v_fmac_f32_e32 v206, v207, v223
	v_lshl_add_u64 v[106:107], v[98:99], 0, v[106:107]
	v_lshl_add_u64 v[104:105], v[98:99], 0, v[104:105]
	v_lshl_add_u64 v[102:103], v[98:99], 0, v[102:103]
	v_fmac_f32_e32 v205, v206, v222
	v_lshl_add_u64 v[100:101], v[98:99], 0, v[100:101]
	v_cvt_pk_bf16_f32 v227, v191, v191
	global_store_short v[130:131], v227, off
	v_fmac_f32_e32 v204, v205, v221
	v_cvt_pk_bf16_f32 v130, v210, v191
	global_store_short v[128:129], v130, off
	v_cvt_pk_bf16_f32 v128, v209, v191
	v_fmac_f32_e32 v203, v204, v220
	global_store_short v[126:127], v128, off
	v_cvt_pk_bf16_f32 v126, v207, v191
	global_store_short v[124:125], v126, off
	v_fmac_f32_e32 v199, v203, v219
	v_cvt_pk_bf16_f32 v124, v206, v191
	global_store_short v[122:123], v124, off
	v_cvt_pk_bf16_f32 v122, v205, v191
	v_fmac_f32_e32 v189, v199, v218
	global_store_short v[120:121], v122, off
	v_cvt_pk_bf16_f32 v120, v204, v191
	global_store_short v[118:119], v120, off
	v_fmac_f32_e32 v188, v189, v217
	v_cvt_pk_bf16_f32 v118, v203, v191
	global_store_short v[116:117], v118, off
	v_cvt_pk_bf16_f32 v116, v199, v191
	v_fmac_f32_e32 v187, v188, v216
	global_store_short v[114:115], v116, off
	v_cvt_pk_bf16_f32 v114, v189, v191
	global_store_short v[112:113], v114, off
	v_fmac_f32_e32 v186, v187, v215
	v_cvt_pk_bf16_f32 v112, v188, v191
	global_store_short v[110:111], v112, off
	v_cvt_pk_bf16_f32 v110, v187, v191
	v_fmac_f32_e32 v185, v186, v214
	global_store_short v[108:109], v110, off
	v_cvt_pk_bf16_f32 v108, v186, v191
	global_store_short v[106:107], v108, off
	v_fmac_f32_e32 v184, v185, v213
	v_cvt_pk_bf16_f32 v106, v185, v191
	global_store_short v[104:105], v106, off
	v_cvt_pk_bf16_f32 v104, v184, v191
	global_store_short v[102:103], v104, off
	v_fmac_f32_e32 v183, v184, v212
	v_cvt_pk_bf16_f32 v102, v183, v191
	global_store_short v[100:101], v102, off
	v_lshl_or_b32 v100, v96, 2, v208
	v_ashrrev_i32_e32 v193, 31, v192
	v_ashrrev_i32_e32 v101, 31, v100
	v_lshl_add_u64 v[192:193], v[192:193], 2, s[76:77]
	v_lshl_add_u64 v[100:101], v[100:101], 2, s[76:77]
	global_load_dword v211, v[192:193], off
	global_load_dword v108, v[100:101], off
	v_lshl_or_b32 v100, v94, 2, v208
	v_ashrrev_i32_e32 v101, 31, v100
	v_lshl_add_u64 v[100:101], v[100:101], 2, s[76:77]
	global_load_dword v109, v[100:101], off
	v_lshl_or_b32 v100, v92, 2, v208
	v_ashrrev_i32_e32 v101, 31, v100
	v_lshl_add_u64 v[100:101], v[100:101], 2, s[76:77]
	global_load_dword v110, v[100:101], off
	v_lshl_or_b32 v100, v90, 2, v208
	v_ashrrev_i32_e32 v101, 31, v100
	v_lshl_add_u64 v[100:101], v[100:101], 2, s[76:77]
	global_load_dword v111, v[100:101], off
	v_lshl_or_b32 v100, v88, 2, v208
	v_ashrrev_i32_e32 v101, 31, v100
	v_lshl_add_u64 v[100:101], v[100:101], 2, s[76:77]
	global_load_dword v112, v[100:101], off
	v_lshl_or_b32 v100, v86, 2, v208
	v_ashrrev_i32_e32 v101, 31, v100
	v_lshl_add_u64 v[100:101], v[100:101], 2, s[76:77]
	global_load_dword v113, v[100:101], off
	v_lshl_or_b32 v100, v84, 2, v208
	v_ashrrev_i32_e32 v101, 31, v100
	v_lshl_add_u64 v[100:101], v[100:101], 2, s[76:77]
	global_load_dword v114, v[100:101], off
	v_lshl_or_b32 v100, v82, 2, v208
	v_ashrrev_i32_e32 v101, 31, v100
	v_lshl_add_u64 v[100:101], v[100:101], 2, s[76:77]
	global_load_dword v115, v[100:101], off
	v_lshl_or_b32 v100, v80, 2, v208
	v_ashrrev_i32_e32 v101, 31, v100
	v_lshl_add_u64 v[100:101], v[100:101], 2, s[76:77]
	global_load_dword v116, v[100:101], off
	v_lshl_or_b32 v100, v78, 2, v208
	v_ashrrev_i32_e32 v101, 31, v100
	v_lshl_add_u64 v[100:101], v[100:101], 2, s[76:77]
	global_load_dword v117, v[100:101], off
	v_lshl_or_b32 v100, v76, 2, v208
	v_ashrrev_i32_e32 v101, 31, v100
	v_lshl_add_u64 v[100:101], v[100:101], 2, s[76:77]
	global_load_dword v105, v[100:101], off
	v_lshl_or_b32 v100, v74, 2, v208
	v_ashrrev_i32_e32 v101, 31, v100
	v_lshl_add_u64 v[100:101], v[100:101], 2, s[76:77]
	global_load_dword v104, v[100:101], off
	v_lshl_or_b32 v100, v72, 2, v208
	v_ashrrev_i32_e32 v101, 31, v100
	v_lshl_add_u64 v[100:101], v[100:101], 2, s[76:77]
	global_load_dword v103, v[100:101], off
	v_lshl_or_b32 v100, v70, 2, v208
	v_ashrrev_i32_e32 v101, 31, v100
	v_lshl_add_u64 v[100:101], v[100:101], 2, s[76:77]
	global_load_dword v102, v[100:101], off
	v_lshl_or_b32 v100, v68, 2, v208
	v_ashrrev_i32_e32 v101, 31, v100
	v_lshl_add_u64 v[100:101], v[100:101], 2, s[76:77]
	global_load_dword v101, v[100:101], off
	v_lshl_or_b32 v106, v66, 2, v208
	v_ashrrev_i32_e32 v107, 31, v106
	v_lshlrev_b64 v[96:97], 16, v[96:97]
	v_lshlrev_b64 v[94:95], 16, v[94:95]
	v_lshlrev_b64 v[92:93], 16, v[92:93]
	v_lshlrev_b64 v[90:91], 16, v[90:91]
	v_lshlrev_b64 v[88:89], 16, v[88:89]
	v_lshlrev_b64 v[86:87], 16, v[86:87]
	v_lshlrev_b64 v[84:85], 16, v[84:85]
	v_lshlrev_b64 v[82:83], 16, v[82:83]
	v_lshlrev_b64 v[80:81], 16, v[80:81]
	v_lshlrev_b64 v[78:79], 16, v[78:79]
	v_lshlrev_b64 v[76:77], 16, v[76:77]
	v_lshlrev_b64 v[74:75], 16, v[74:75]
	v_lshlrev_b64 v[72:73], 16, v[72:73]
	v_lshlrev_b64 v[70:71], 16, v[70:71]
	v_lshlrev_b64 v[68:69], 16, v[68:69]
	v_lshlrev_b64 v[66:67], 16, v[66:67]
	v_lshl_add_u64 v[106:107], v[106:107], 2, s[76:77]
	v_lshl_add_u64 v[96:97], v[98:99], 0, v[96:97]
	v_lshl_add_u64 v[94:95], v[98:99], 0, v[94:95]
	v_lshl_add_u64 v[92:93], v[98:99], 0, v[92:93]
	s_waitcnt vmcnt(0)
	v_fmac_f32_e32 v182, v183, v211
	s_waitcnt vmcnt(14)
	v_fmac_f32_e32 v181, v182, v108
	v_lshl_add_u64 v[90:91], v[98:99], 0, v[90:91]
	v_lshl_add_u64 v[88:89], v[98:99], 0, v[88:89]
	v_lshl_add_u64 v[86:87], v[98:99], 0, v[86:87]
	s_waitcnt vmcnt(13)
	v_fmac_f32_e32 v180, v181, v109
	v_lshl_add_u64 v[84:85], v[98:99], 0, v[84:85]
	v_lshl_add_u64 v[82:83], v[98:99], 0, v[82:83]
	v_lshl_add_u64 v[80:81], v[98:99], 0, v[80:81]
	s_waitcnt vmcnt(12)
	v_fmac_f32_e32 v179, v180, v110
	v_lshl_add_u64 v[78:79], v[98:99], 0, v[78:79]
	v_lshl_add_u64 v[76:77], v[98:99], 0, v[76:77]
	v_lshl_add_u64 v[74:75], v[98:99], 0, v[74:75]
	s_waitcnt vmcnt(11)
	v_fmac_f32_e32 v178, v179, v111
	v_lshl_add_u64 v[72:73], v[98:99], 0, v[72:73]
	v_lshl_add_u64 v[70:71], v[98:99], 0, v[70:71]
	v_lshl_add_u64 v[68:69], v[98:99], 0, v[68:69]
	s_waitcnt vmcnt(10)
	v_fmac_f32_e32 v177, v178, v112
	v_lshl_add_u64 v[66:67], v[98:99], 0, v[66:67]
	global_load_dword v100, v[106:107], off
	v_cvt_pk_bf16_f32 v106, v182, v191
	s_waitcnt vmcnt(10)
	v_fmac_f32_e32 v176, v177, v113
	global_store_short v[96:97], v106, off
	v_cvt_pk_bf16_f32 v96, v181, v191
	global_store_short v[94:95], v96, off
	s_waitcnt vmcnt(11)
	v_fmac_f32_e32 v175, v176, v114
	v_cvt_pk_bf16_f32 v94, v180, v191
	global_store_short v[92:93], v94, off
	v_cvt_pk_bf16_f32 v92, v179, v191
	s_waitcnt vmcnt(11)
	v_fmac_f32_e32 v174, v175, v115
	global_store_short v[90:91], v92, off
	v_cvt_pk_bf16_f32 v90, v178, v191
	global_store_short v[88:89], v90, off
	s_waitcnt vmcnt(12)
	v_fmac_f32_e32 v173, v174, v116
	v_cvt_pk_bf16_f32 v88, v177, v191
	global_store_short v[86:87], v88, off
	v_cvt_pk_bf16_f32 v86, v176, v191
	s_waitcnt vmcnt(12)
	v_fmac_f32_e32 v172, v173, v117
	global_store_short v[84:85], v86, off
	v_cvt_pk_bf16_f32 v84, v175, v191
	global_store_short v[82:83], v84, off
	s_waitcnt vmcnt(13)
	v_fmac_f32_e32 v171, v172, v105
	v_cvt_pk_bf16_f32 v82, v174, v191
	global_store_short v[80:81], v82, off
	v_cvt_pk_bf16_f32 v80, v173, v191
	s_waitcnt vmcnt(13)
	v_fmac_f32_e32 v170, v171, v104
	global_store_short v[78:79], v80, off
	v_cvt_pk_bf16_f32 v78, v172, v191
	global_store_short v[76:77], v78, off
	s_waitcnt vmcnt(14)
	v_fmac_f32_e32 v169, v170, v103
	v_cvt_pk_bf16_f32 v76, v171, v191
	global_store_short v[74:75], v76, off
	v_cvt_pk_bf16_f32 v74, v170, v191
	s_waitcnt vmcnt(14)
	v_fmac_f32_e32 v168, v169, v102
	global_store_short v[72:73], v74, off
	v_cvt_pk_bf16_f32 v72, v169, v191
	global_store_short v[70:71], v72, off
	v_cvt_pk_bf16_f32 v70, v168, v191
	global_store_short v[68:69], v70, off
	s_waitcnt vmcnt(16)
	v_fmac_f32_e32 v167, v168, v101
	v_cvt_pk_bf16_f32 v68, v167, v191
	global_store_short v[66:67], v68, off
	v_lshl_or_b32 v66, v64, 2, v208
	v_ashrrev_i32_e32 v67, 31, v66
	v_lshl_add_u64 v[66:67], v[66:67], 2, s[76:77]
	global_load_dword v74, v[66:67], off
	v_lshl_or_b32 v66, v62, 2, v208
	v_ashrrev_i32_e32 v67, 31, v66
	v_lshl_add_u64 v[66:67], v[66:67], 2, s[76:77]
	global_load_dword v75, v[66:67], off
	v_lshl_or_b32 v66, v60, 2, v208
	v_ashrrev_i32_e32 v67, 31, v66
	v_lshl_add_u64 v[66:67], v[66:67], 2, s[76:77]
	global_load_dword v76, v[66:67], off
	v_lshl_or_b32 v66, v58, 2, v208
	v_ashrrev_i32_e32 v67, 31, v66
	v_lshl_add_u64 v[66:67], v[66:67], 2, s[76:77]
	global_load_dword v77, v[66:67], off
	v_lshl_or_b32 v66, v56, 2, v208
	v_ashrrev_i32_e32 v67, 31, v66
	v_lshl_add_u64 v[66:67], v[66:67], 2, s[76:77]
	global_load_dword v78, v[66:67], off
	v_lshl_or_b32 v66, v54, 2, v208
	v_ashrrev_i32_e32 v67, 31, v66
	v_lshl_add_u64 v[66:67], v[66:67], 2, s[76:77]
	global_load_dword v79, v[66:67], off
	v_lshl_or_b32 v66, v52, 2, v208
	v_ashrrev_i32_e32 v67, 31, v66
	v_lshl_add_u64 v[66:67], v[66:67], 2, s[76:77]
	global_load_dword v80, v[66:67], off
	v_lshl_or_b32 v66, v50, 2, v208
	v_ashrrev_i32_e32 v67, 31, v66
	v_lshl_add_u64 v[66:67], v[66:67], 2, s[76:77]
	global_load_dword v81, v[66:67], off
	v_lshl_or_b32 v66, v48, 2, v208
	v_ashrrev_i32_e32 v67, 31, v66
	v_lshl_add_u64 v[66:67], v[66:67], 2, s[76:77]
	global_load_dword v82, v[66:67], off
	v_lshl_or_b32 v66, v46, 2, v208
	v_ashrrev_i32_e32 v67, 31, v66
	v_lshl_add_u64 v[66:67], v[66:67], 2, s[76:77]
	global_load_dword v83, v[66:67], off
	v_lshl_or_b32 v66, v44, 2, v208
	v_ashrrev_i32_e32 v67, 31, v66
	v_lshl_add_u64 v[66:67], v[66:67], 2, s[76:77]
	global_load_dword v71, v[66:67], off
	v_lshl_or_b32 v66, v42, 2, v208
	v_ashrrev_i32_e32 v67, 31, v66
	v_lshl_add_u64 v[66:67], v[66:67], 2, s[76:77]
	global_load_dword v70, v[66:67], off
	v_lshl_or_b32 v66, v40, 2, v208
	v_ashrrev_i32_e32 v67, 31, v66
	v_lshl_add_u64 v[66:67], v[66:67], 2, s[76:77]
	global_load_dword v69, v[66:67], off
	v_lshl_or_b32 v66, v38, 2, v208
	v_ashrrev_i32_e32 v67, 31, v66
	v_lshl_add_u64 v[66:67], v[66:67], 2, s[76:77]
	global_load_dword v68, v[66:67], off
	v_lshl_or_b32 v66, v36, 2, v208
	v_ashrrev_i32_e32 v67, 31, v66
	v_lshl_add_u64 v[66:67], v[66:67], 2, s[76:77]
	global_load_dword v67, v[66:67], off
	s_waitcnt vmcnt(0)
	v_fmac_f32_e32 v166, v167, v100
	v_lshl_or_b32 v72, v34, 2, v208
	v_ashrrev_i32_e32 v73, 31, v72
	v_lshlrev_b64 v[64:65], 16, v[64:65]
	v_lshlrev_b64 v[62:63], 16, v[62:63]
	v_lshlrev_b64 v[60:61], 16, v[60:61]
	v_lshlrev_b64 v[58:59], 16, v[58:59]
	v_lshlrev_b64 v[56:57], 16, v[56:57]
	v_lshlrev_b64 v[54:55], 16, v[54:55]
	v_lshlrev_b64 v[52:53], 16, v[52:53]
	v_lshlrev_b64 v[50:51], 16, v[50:51]
	v_lshlrev_b64 v[48:49], 16, v[48:49]
	v_lshlrev_b64 v[46:47], 16, v[46:47]
	v_lshlrev_b64 v[44:45], 16, v[44:45]
	v_lshlrev_b64 v[42:43], 16, v[42:43]
	v_lshlrev_b64 v[40:41], 16, v[40:41]
	v_lshlrev_b64 v[38:39], 16, v[38:39]
	v_lshlrev_b64 v[36:37], 16, v[36:37]
	v_lshlrev_b64 v[34:35], 16, v[34:35]
	v_lshl_add_u64 v[72:73], v[72:73], 2, s[76:77]
	v_lshl_add_u64 v[64:65], v[98:99], 0, v[64:65]
	v_lshl_add_u64 v[62:63], v[98:99], 0, v[62:63]
	v_lshl_add_u64 v[60:61], v[98:99], 0, v[60:61]
	s_waitcnt vmcnt(14)
	v_fmac_f32_e32 v165, v166, v74
	v_lshl_add_u64 v[58:59], v[98:99], 0, v[58:59]
	v_lshl_add_u64 v[56:57], v[98:99], 0, v[56:57]
	v_lshl_add_u64 v[54:55], v[98:99], 0, v[54:55]
	s_waitcnt vmcnt(13)
	v_fmac_f32_e32 v164, v165, v75
	v_lshl_add_u64 v[52:53], v[98:99], 0, v[52:53]
	v_lshl_add_u64 v[50:51], v[98:99], 0, v[50:51]
	v_lshl_add_u64 v[48:49], v[98:99], 0, v[48:49]
	s_waitcnt vmcnt(12)
	v_fmac_f32_e32 v163, v164, v76
	v_lshl_add_u64 v[46:47], v[98:99], 0, v[46:47]
	v_lshl_add_u64 v[44:45], v[98:99], 0, v[44:45]
	v_lshl_add_u64 v[42:43], v[98:99], 0, v[42:43]
	s_waitcnt vmcnt(11)
	v_fmac_f32_e32 v162, v163, v77
	v_lshl_add_u64 v[40:41], v[98:99], 0, v[40:41]
	v_lshl_add_u64 v[38:39], v[98:99], 0, v[38:39]
	v_lshl_add_u64 v[36:37], v[98:99], 0, v[36:37]
	s_waitcnt vmcnt(10)
	v_fmac_f32_e32 v161, v162, v78
	v_lshl_add_u64 v[34:35], v[98:99], 0, v[34:35]
	global_load_dword v66, v[72:73], off
	v_cvt_pk_bf16_f32 v72, v166, v191
	s_waitcnt vmcnt(10)
	v_fmac_f32_e32 v160, v161, v79
	global_store_short v[64:65], v72, off
	v_cvt_pk_bf16_f32 v64, v165, v191
	global_store_short v[62:63], v64, off
	s_waitcnt vmcnt(11)
	v_fmac_f32_e32 v159, v160, v80
	v_cvt_pk_bf16_f32 v62, v164, v191
	global_store_short v[60:61], v62, off
	v_cvt_pk_bf16_f32 v60, v163, v191
	s_waitcnt vmcnt(11)
	v_fmac_f32_e32 v158, v159, v81
	global_store_short v[58:59], v60, off
	v_cvt_pk_bf16_f32 v58, v162, v191
	global_store_short v[56:57], v58, off
	s_waitcnt vmcnt(12)
	v_fmac_f32_e32 v157, v158, v82
	v_cvt_pk_bf16_f32 v56, v161, v191
	global_store_short v[54:55], v56, off
	v_cvt_pk_bf16_f32 v54, v160, v191
	s_waitcnt vmcnt(12)
	v_fmac_f32_e32 v156, v157, v83
	global_store_short v[52:53], v54, off
	v_cvt_pk_bf16_f32 v52, v159, v191
	global_store_short v[50:51], v52, off
	s_waitcnt vmcnt(13)
	v_fmac_f32_e32 v155, v156, v71
	v_cvt_pk_bf16_f32 v50, v158, v191
	global_store_short v[48:49], v50, off
	v_cvt_pk_bf16_f32 v48, v157, v191
	s_waitcnt vmcnt(13)
	v_fmac_f32_e32 v154, v155, v70
	global_store_short v[46:47], v48, off
	v_cvt_pk_bf16_f32 v46, v156, v191
	global_store_short v[44:45], v46, off
	s_waitcnt vmcnt(14)
	v_fmac_f32_e32 v153, v154, v69
	v_cvt_pk_bf16_f32 v44, v155, v191
	global_store_short v[42:43], v44, off
	v_cvt_pk_bf16_f32 v42, v154, v191
	s_waitcnt vmcnt(14)
	v_fmac_f32_e32 v152, v153, v68
	global_store_short v[40:41], v42, off
	v_cvt_pk_bf16_f32 v40, v153, v191
	global_store_short v[38:39], v40, off
	v_cvt_pk_bf16_f32 v38, v152, v191
	global_store_short v[36:37], v38, off
	s_waitcnt vmcnt(16)
	v_fmac_f32_e32 v151, v152, v67
	v_cvt_pk_bf16_f32 v36, v151, v191
	global_store_short v[34:35], v36, off
	v_lshl_or_b32 v34, v32, 2, v208
	v_ashrrev_i32_e32 v35, 31, v34
	v_lshl_add_u64 v[34:35], v[34:35], 2, s[76:77]
	global_load_dword v42, v[34:35], off
	v_lshl_or_b32 v34, v30, 2, v208
	v_ashrrev_i32_e32 v35, 31, v34
	v_lshl_add_u64 v[34:35], v[34:35], 2, s[76:77]
	global_load_dword v43, v[34:35], off
	v_lshl_or_b32 v34, v28, 2, v208
	v_ashrrev_i32_e32 v35, 31, v34
	v_lshl_add_u64 v[34:35], v[34:35], 2, s[76:77]
	global_load_dword v44, v[34:35], off
	v_lshl_or_b32 v34, v26, 2, v208
	v_ashrrev_i32_e32 v35, 31, v34
	v_lshl_add_u64 v[34:35], v[34:35], 2, s[76:77]
	global_load_dword v45, v[34:35], off
	v_lshl_or_b32 v34, v24, 2, v208
	v_ashrrev_i32_e32 v35, 31, v34
	v_lshl_add_u64 v[34:35], v[34:35], 2, s[76:77]
	global_load_dword v46, v[34:35], off
	v_lshl_or_b32 v34, v22, 2, v208
	v_ashrrev_i32_e32 v35, 31, v34
	v_lshl_add_u64 v[34:35], v[34:35], 2, s[76:77]
	global_load_dword v47, v[34:35], off
	v_lshl_or_b32 v34, v20, 2, v208
	v_ashrrev_i32_e32 v35, 31, v34
	v_lshl_add_u64 v[34:35], v[34:35], 2, s[76:77]
	global_load_dword v48, v[34:35], off
	v_lshl_or_b32 v34, v18, 2, v208
	v_ashrrev_i32_e32 v35, 31, v34
	v_lshl_add_u64 v[34:35], v[34:35], 2, s[76:77]
	global_load_dword v49, v[34:35], off
	v_lshl_or_b32 v34, v16, 2, v208
	v_ashrrev_i32_e32 v35, 31, v34
	v_lshl_add_u64 v[34:35], v[34:35], 2, s[76:77]
	global_load_dword v50, v[34:35], off
	v_lshl_or_b32 v34, v14, 2, v208
	v_ashrrev_i32_e32 v35, 31, v34
	v_lshl_add_u64 v[34:35], v[34:35], 2, s[76:77]
	global_load_dword v51, v[34:35], off
	v_lshl_or_b32 v34, v12, 2, v208
	v_ashrrev_i32_e32 v35, 31, v34
	v_lshl_add_u64 v[34:35], v[34:35], 2, s[76:77]
	global_load_dword v39, v[34:35], off
	v_lshl_or_b32 v34, v10, 2, v208
	v_ashrrev_i32_e32 v35, 31, v34
	v_lshl_add_u64 v[34:35], v[34:35], 2, s[76:77]
	global_load_dword v38, v[34:35], off
	v_lshl_or_b32 v34, v8, 2, v208
	v_ashrrev_i32_e32 v35, 31, v34
	v_lshl_add_u64 v[34:35], v[34:35], 2, s[76:77]
	global_load_dword v37, v[34:35], off
	v_lshl_or_b32 v34, v6, 2, v208
	v_ashrrev_i32_e32 v35, 31, v34
	v_lshl_add_u64 v[34:35], v[34:35], 2, s[76:77]
	global_load_dword v36, v[34:35], off
	v_lshl_or_b32 v34, v4, 2, v208
	v_ashrrev_i32_e32 v35, 31, v34
	v_lshl_add_u64 v[34:35], v[34:35], 2, s[76:77]
	global_load_dword v35, v[34:35], off
	v_lshl_or_b32 v40, v2, 2, v208
	v_ashrrev_i32_e32 v41, 31, v40
	v_lshl_add_u64 v[40:41], v[40:41], 2, s[76:77]
	global_load_dword v34, v[40:41], off
	s_waitcnt vmcnt(0)
	v_fmac_f32_e32 v150, v151, v66
	v_lshlrev_b64 v[32:33], 16, v[32:33]
	v_lshlrev_b64 v[30:31], 16, v[30:31]
	v_lshlrev_b64 v[28:29], 16, v[28:29]
	v_lshlrev_b64 v[26:27], 16, v[26:27]
	v_lshlrev_b64 v[24:25], 16, v[24:25]
	v_lshlrev_b64 v[22:23], 16, v[22:23]
	v_lshlrev_b64 v[20:21], 16, v[20:21]
	v_lshlrev_b64 v[18:19], 16, v[18:19]
	v_lshlrev_b64 v[16:17], 16, v[16:17]
	v_lshlrev_b64 v[14:15], 16, v[14:15]
	v_lshlrev_b64 v[12:13], 16, v[12:13]
	v_lshlrev_b64 v[10:11], 16, v[10:11]
	v_lshlrev_b64 v[8:9], 16, v[8:9]
	v_lshlrev_b64 v[6:7], 16, v[6:7]
	v_lshlrev_b64 v[4:5], 16, v[4:5]
	v_lshlrev_b64 v[2:3], 16, v[2:3]
	v_lshl_add_u64 v[32:33], v[98:99], 0, v[32:33]
	v_lshl_add_u64 v[30:31], v[98:99], 0, v[30:31]
	s_waitcnt vmcnt(15)
	v_fmac_f32_e32 v149, v150, v42
	v_lshl_add_u64 v[28:29], v[98:99], 0, v[28:29]
	v_lshl_add_u64 v[26:27], v[98:99], 0, v[26:27]
	v_lshl_add_u64 v[24:25], v[98:99], 0, v[24:25]
	s_waitcnt vmcnt(14)
	v_fmac_f32_e32 v148, v149, v43
	v_lshl_add_u64 v[22:23], v[98:99], 0, v[22:23]
	v_lshl_add_u64 v[20:21], v[98:99], 0, v[20:21]
	v_lshl_add_u64 v[18:19], v[98:99], 0, v[18:19]
	s_waitcnt vmcnt(13)
	v_fmac_f32_e32 v147, v148, v44
	v_lshl_add_u64 v[16:17], v[98:99], 0, v[16:17]
	v_lshl_add_u64 v[14:15], v[98:99], 0, v[14:15]
	v_lshl_add_u64 v[12:13], v[98:99], 0, v[12:13]
	s_waitcnt vmcnt(12)
	v_fmac_f32_e32 v146, v147, v45
	v_lshl_add_u64 v[10:11], v[98:99], 0, v[10:11]
	v_lshl_add_u64 v[8:9], v[98:99], 0, v[8:9]
	v_lshl_add_u64 v[6:7], v[98:99], 0, v[6:7]
	s_waitcnt vmcnt(11)
	v_fmac_f32_e32 v145, v146, v46
	v_lshl_add_u64 v[4:5], v[98:99], 0, v[4:5]
	v_lshl_add_u64 v[2:3], v[98:99], 0, v[2:3]
	v_cvt_pk_bf16_f32 v40, v150, v191
	s_waitcnt vmcnt(10)
	v_fmac_f32_e32 v144, v145, v47
	global_store_short v[32:33], v40, off
	v_cvt_pk_bf16_f32 v32, v149, v191
	global_store_short v[30:31], v32, off
	s_waitcnt vmcnt(11)
	v_fmac_f32_e32 v143, v144, v48
	v_cvt_pk_bf16_f32 v30, v148, v191
	global_store_short v[28:29], v30, off
	v_cvt_pk_bf16_f32 v28, v147, v191
	s_waitcnt vmcnt(11)
	v_fmac_f32_e32 v142, v143, v49
	global_store_short v[26:27], v28, off
	v_cvt_pk_bf16_f32 v26, v146, v191
	global_store_short v[24:25], v26, off
	s_waitcnt vmcnt(12)
	v_fmac_f32_e32 v141, v142, v50
	v_cvt_pk_bf16_f32 v24, v145, v191
	global_store_short v[22:23], v24, off
	v_cvt_pk_bf16_f32 v22, v144, v191
	s_waitcnt vmcnt(12)
	v_fmac_f32_e32 v140, v141, v51
	global_store_short v[20:21], v22, off
	v_cvt_pk_bf16_f32 v20, v143, v191
	global_store_short v[18:19], v20, off
	s_waitcnt vmcnt(13)
	v_fmac_f32_e32 v139, v140, v39
	v_cvt_pk_bf16_f32 v18, v142, v191
	global_store_short v[16:17], v18, off
	v_cvt_pk_bf16_f32 v16, v141, v191
	s_waitcnt vmcnt(13)
	v_fmac_f32_e32 v138, v139, v38
	global_store_short v[14:15], v16, off
	v_cvt_pk_bf16_f32 v14, v140, v191
	global_store_short v[12:13], v14, off
	s_waitcnt vmcnt(14)
	v_fmac_f32_e32 v137, v138, v37
	v_cvt_pk_bf16_f32 v12, v139, v191
	global_store_short v[10:11], v12, off
	v_cvt_pk_bf16_f32 v10, v138, v191
	s_waitcnt vmcnt(14)
	v_fmac_f32_e32 v136, v137, v36
	global_store_short v[8:9], v10, off
	v_cvt_pk_bf16_f32 v8, v137, v191
	global_store_short v[6:7], v8, off
	v_cvt_pk_bf16_f32 v6, v136, v191
	global_store_short v[4:5], v6, off
	s_waitcnt vmcnt(16)
	v_fmac_f32_e32 v135, v136, v35
	v_cvt_pk_bf16_f32 v4, v135, v191
	global_store_short v[2:3], v4, off
	v_add_u32_e32 v2, s4, v134
	v_ashrrev_i32_e32 v3, 31, v2
	v_lshlrev_b64 v[2:3], 17, v[2:3]
	v_lshl_add_u64 v[2:3], s[20:21], 0, v[2:3]
	v_lshl_add_u64 v[2:3], v[2:3], 0, v[190:191]
	v_add_co_u32_e32 v2, vcc, 0x4200000, v2
	s_waitcnt vmcnt(16)
	v_fmac_f32_e32 v133, v135, v34
	v_addc_co_u32_e32 v3, vcc, 0, v3, vcc
	global_store_dword v[2:3], v133, off
	s_load_dword s5, s[66:67], 0x0
	s_waitcnt lgkmcnt(0)
	v_lshl_add_u32 v132, s5, 9, v132
	s_mov_b32 s5, 0x1ffff
	v_cmp_lt_i32_e32 vcc, s5, v132
	s_or_b64 s[2:3], vcc, s[2:3]
	s_andn2_b64 exec, exec, s[2:3]
	s_cbranch_execnz .LBB0_439

.LBB0_1003:
	v_ashrrev_i32_e32 v9, 7, v3
	v_ashrrev_i32_e32 v11, 2, v3
	v_and_b32_e32 v10, 0x7f, v9
	v_and_b32_e32 v11, 0xfffff000, v11
	s_movk_i32 s1, 0xf80
	v_or3_b32 v10, v11, v10, s1
	v_ashrrev_i32_e32 v11, 31, v10
	v_lshlrev_b64 v[10:11], 12, v[10:11]
	v_lshl_add_u64 v[10:11], v[4:5], 0, v[10:11]
	global_load_ushort v12, v[10:11], off offset:2048
	global_load_ushort v14, v[10:11], off offset:2304
	v_add_u32_e32 v16, 0x4000, v9
	v_ashrrev_i32_e32 v17, 31, v16
	v_lshlrev_b64 v[16:17], 12, v[16:17]
	v_lshl_add_u64 v[16:17], v[4:5], 0, v[16:17]
	global_load_ushort v15, v[16:17], off offset:2048
	global_load_ushort v18, v[16:17], off offset:2304
	s_mov_b32 s1, 0x100000
	v_add_u32_e32 v3, s0, v3
	s_waitcnt vmcnt(0)
	v_lshlrev_b32_e32 v12, 16, v12
	global_store_dword v[6:7], v12, off
	v_lshlrev_b32_e32 v12, 16, v14
	v_add_co_u32_e32 v10, vcc, s1, v6
	s_mov_b32 s1, 0xffff
	s_nop 0
	v_addc_co_u32_e32 v11, vcc, 0, v7, vcc
	global_store_dword v[10:11], v12, off
	v_add_co_u32_e32 v12, vcc, 0x80000, v6
	v_lshlrev_b32_e32 v9, 16, v15
	s_nop 0
	v_addc_co_u32_e32 v13, vcc, 0, v7, vcc
	global_store_dword v[12:13], v9, off
	v_add_co_u32_e32 v10, vcc, 0x180000, v6
	v_lshlrev_b32_e32 v9, 16, v18
	s_nop 0
	v_addc_co_u32_e32 v11, vcc, 0, v7, vcc
	v_cmp_lt_i32_e32 vcc, s1, v3
	v_lshl_add_u64 v[6:7], v[6:7], 0, s[6:7]
	s_or_b64 s[8:9], vcc, s[8:9]
	global_store_dword v[10:11], v9, off
	s_andn2_b64 exec, exec, s[8:9]
	s_cbranch_execnz .LBB0_1003
